# all three GEMM main loops hand-written (3-stage LDS-DMA ring); gemm2 epilogues with x loads hoisted; gemm1 f32 write-out batched; half-grid stagger in the in-proj phase
# speedup vs baseline: 1.0031x; 1.0031x over previous
.LBB0_254:
	s_lshl_b32 s0, s38, 7
	s_or_b32 s46, s0, s56
	v_cmp_gt_i64_e64 s[38:39], s[34:35], -1
	s_and_b32 s48, s46, 0x1c0
	s_and_b64 vcc, exec, s[38:39]
	ds_write_b128 v101, v[42:45] offset:192
	ds_write_b128 v101, v[46:49] offset:224
	s_cbranch_vccz .LBB0_256
	s_add_i32 s0, s65, 0xffffc000
	s_and_b64 s[66:67], s[6:7], exec
	s_cselect_b32 s47, s65, s0
	s_lshl_b64 s[66:67], s[34:35], 2
	s_add_u32 s66, s68, s66
	s_addc_u32 s67, s69, s67
	s_lshl_b32 s0, s48, 2
	v_or_b32_e32 v156, s47, v209
	v_lshlrev_b32_e32 v156, 11, v156
	v_lshl_add_u32 v182, v188, 2, s0
	v_add_u32_e32 v148, v156, v182
	v_add_u32_e32 v149, 0x2000, v148
	v_add_u32_e32 v150, 0x4000, v148
	v_add_u32_e32 v151, 0x6000, v148
	v_add_u32_e32 v152, 0x8000, v148
	v_add_u32_e32 v153, 0xa000, v148
	v_add_u32_e32 v154, 0xc000, v148
	v_add_u32_e32 v155, 0xe000, v148
	ds_read_b128 v[158:161], v102
	ds_read_b128 v[162:165], v102 offset:1088
	ds_read_b128 v[166:169], v102 offset:2176
	ds_read_b128 v[170:173], v102 offset:3264
	ds_read_b128 v[174:177], v102 offset:4352
	ds_read_b128 v[178:181], v102 offset:5440
	ds_read_b128 v[190:193], v102 offset:6528
	ds_read_b128 v[194:197], v102 offset:7616
	s_waitcnt lgkmcnt(7)
	global_store_dwordx4 v148, v[158:161], s[66:67]
	s_waitcnt lgkmcnt(6)
	global_store_dwordx4 v149, v[162:165], s[66:67]
	s_waitcnt lgkmcnt(5)
	global_store_dwordx4 v150, v[166:169], s[66:67]
	s_waitcnt lgkmcnt(4)
	global_store_dwordx4 v151, v[170:173], s[66:67]
	s_waitcnt lgkmcnt(3)
	global_store_dwordx4 v152, v[174:177], s[66:67]
	s_waitcnt lgkmcnt(2)
	global_store_dwordx4 v153, v[178:181], s[66:67]
	s_waitcnt lgkmcnt(1)
	global_store_dwordx4 v154, v[190:193], s[66:67]
	s_waitcnt lgkmcnt(0)
	global_store_dwordx4 v155, v[194:197], s[66:67]

.LBB0_289:
	s_addk_i32 s65, 0xc020
	s_and_b64 s[6:7], s[6:7], exec
	s_cselect_b32 s8, s40, s65
	s_lshl_b64 s[6:7], s[34:35], 2
	s_add_u32 s6, s68, s6
	s_addc_u32 s7, s69, s7
	s_lshl_b32 s0, s48, 2
	v_or_b32_e32 v156, s8, v209
	v_lshlrev_b32_e32 v156, 11, v156
	v_lshl_add_u32 v182, v188, 2, s0
	v_add_u32_e32 v148, v156, v182
	v_add_u32_e32 v149, 0x2000, v148
	v_add_u32_e32 v150, 0x4000, v148
	v_add_u32_e32 v151, 0x6000, v148
	v_add_u32_e32 v152, 0x8000, v148
	v_add_u32_e32 v153, 0xa000, v148
	v_add_u32_e32 v154, 0xc000, v148
	v_add_u32_e32 v155, 0xe000, v148
	ds_read_b128 v[158:161], v102
	ds_read_b128 v[162:165], v102 offset:1088
	ds_read_b128 v[166:169], v102 offset:2176
	ds_read_b128 v[170:173], v102 offset:3264
	ds_read_b128 v[174:177], v102 offset:4352
	ds_read_b128 v[178:181], v102 offset:5440
	ds_read_b128 v[190:193], v102 offset:6528
	ds_read_b128 v[194:197], v102 offset:7616
	s_waitcnt lgkmcnt(7)
	global_store_dwordx4 v148, v[158:161], s[6:7]
	s_waitcnt lgkmcnt(6)
	global_store_dwordx4 v149, v[162:165], s[6:7]
	s_waitcnt lgkmcnt(5)
	global_store_dwordx4 v150, v[166:169], s[6:7]
	s_waitcnt lgkmcnt(4)
	global_store_dwordx4 v151, v[170:173], s[6:7]
	s_waitcnt lgkmcnt(3)
	global_store_dwordx4 v152, v[174:177], s[6:7]
	s_waitcnt lgkmcnt(2)
	global_store_dwordx4 v153, v[178:181], s[6:7]
	s_waitcnt lgkmcnt(1)
	global_store_dwordx4 v154, v[190:193], s[6:7]
	s_waitcnt lgkmcnt(0)
	global_store_dwordx4 v155, v[194:197], s[6:7]
	s_branch .LBB0_208

.LBB0_877:
	s_ashr_i32 s4, s2, 1
	s_add_i32 s4, s4, s3
	s_ashr_i32 s70, s4, 2
	s_lshl_b32 s4, s4, 8
	s_and_b32 s4, s4, 0x300
	s_and_b32 s71, s93, 0x80
	s_or_b32 s96, s4, s71
	v_readfirstlane_b32 s79, v184
	s_nop 3
	s_ashr_i32 s71, s70, 31
	s_lshr_b32 s97, s79, 6
	s_lshl_b64 s[72:73], s[70:71], 18
	s_add_u32 s12, s82, s72
	s_addc_u32 s13, s83, s73
	s_lshl_b32 s4, s96, 11
	s_add_u32 s14, s84, s4
	s_addc_u32 s15, s85, 0
	s_lshr_b32 s4, s79, 4
	s_and_b32 s4, s4, 4
	v_lshl_or_b32 v32, s97, 3, v210
	v_bitop3_b32 v4, s4, v208, v209 bitop3:0x36
	v_lshlrev_b32_e32 v32, 11, v32
	v_lshlrev_b32_e32 v4, 4, v4
	v_or_b32_e32 v154, v32, v4
	v_add_u32_e32 v155, 0x20000, v154
	s_lshl_b32 s19, s97, 10
	s_and_b32 s4, s79, 64
	v_or_b32_e32 v32, s4, v189
	v_lshlrev_b32_e32 v148, 7, v32
	s_lshr_b32 s6, s79, 2
	s_and_b32 s88, s6, 0x3fffffe0
	v_or_b32_e32 v32, s88, v189
	v_lshlrev_b32_e32 v149, 7, v32
	s_lshl_b32 s6, s70, 7
	s_or_b32 s76, s6, s4
	s_cmpk_gt_i32 s76, 0x3fff
	s_cbranch_scc0 .Lg3_prompt
	s_add_i32 s4, s76, 0xffffc000
	s_lshr_b32 s70, s4, 6
	s_mulk_i32 s70, 0xc00
	s_add_i32 s74, s70, 0xc00
	s_lshl_b64 s[72:73], s[4:5], 12
	s_add_u32 s70, s87, s72
	v_readlane_b32 s78, v247, 6
	s_addc_u32 s71, s92, s73
	s_ashr_i32 s75, s74, 31
	v_readlane_b32 s79, v247, 7
	s_nop 3
	s_branch .Lg3_ptr
.Lg3_prompt:
	s_mov_b64 s[78:79], s[90:91]
	s_load_dwordx4 s[8:11], s[90:91], 0xc0
	s_ashr_i32 s77, s76, 31
	s_lshl_b64 s[72:73], s[76:77], 12
	s_mov_b64 s[74:75], 0
	s_waitcnt lgkmcnt(0)
	s_add_u32 s70, s8, s72
	s_addc_u32 s71, s9, s73
.Lg3_ptr:
	s_load_dwordx2 s[76:77], s[78:79], 0x0
	s_load_dwordx4 s[8:11], s[90:91], 0xc0
	s_mulk_i32 s97, 0x3000
	v_mov_b32_e32 v35, v33
	s_waitcnt lgkmcnt(0)
	s_add_u32 s72, s76, s72
	s_addc_u32 s73, s77, s73
	s_lshl_b64 s[74:75], s[74:75], 2
	s_add_u32 s76, s10, s74
	s_addc_u32 s77, s11, s75
	s_add_i32 s4, s96, s88
	s_add_i32 s78, s97, 0x100
	s_lshl_b64 s[74:75], s[4:5], 2
	s_add_u32 s74, s76, s74
	s_addc_u32 s75, s77, s75
	v_lshl_add_u64 v[36:37], s[74:75], 0, v[34:35]
	v_add_co_u32_e32 v48, vcc, s95, v36
	s_nop 1
	v_addc_co_u32_e32 v49, vcc, 0, v37, vcc
	v_add_u32_e32 v72, s4, v43
	v_add_u32_e32 v73, s4, v44
	v_add_u32_e32 v74, s4, v45
	v_add_u32_e32 v75, s4, v46
	v_lshlrev_b32_e32 v72, 2, v72
	v_lshlrev_b32_e32 v73, 2, v73
	v_lshlrev_b32_e32 v74, 2, v74
	v_lshlrev_b32_e32 v75, 2, v75
	s_add_u32 s80, s72, 0x20000
	s_addc_u32 s81, s73, 0
	s_add_u32 s100, s70, 0x20000
	s_addc_u32 s101, s71, 0
	v_add3_u32 v54, s78, v40, v42
	v_add3_u32 v35, s78, v186, v41
	s_movk_i32 s16, 0x100
	s_mov_b32 s17, 0xc100
	s_mov_b32 s18, 0x1b900
	s_add_i32 s21, s16, s19
	s_mov_b32 m0, s21
	s_nop 0
	global_load_lds_dwordx4 v154, s[12:13]
	s_add_i32 m0, s21, 0x2000
	s_nop 0
	global_load_lds_dwordx4 v155, s[12:13]
	s_add_i32 m0, s21, 0x4000
	s_nop 0
	global_load_lds_dwordx4 v154, s[14:15]
	s_add_i32 m0, s21, 0x6000
	s_nop 0
	global_load_lds_dwordx4 v155, s[14:15]
	s_add_u32 s12, s12, 0x80
	s_addc_u32 s13, s13, 0
	s_add_u32 s14, s14, 0x80
	s_addc_u32 s15, s15, 0
	s_add_i32 s21, s17, s19
	s_mov_b32 m0, s21
	s_nop 0
	global_load_lds_dwordx4 v154, s[12:13]
	s_add_i32 m0, s21, 0x2000
	s_nop 0
	global_load_lds_dwordx4 v155, s[12:13]
	s_add_i32 m0, s21, 0x4000
	s_nop 0
	global_load_lds_dwordx4 v154, s[14:15]
	s_add_i32 m0, s21, 0x6000
	s_nop 0
	global_load_lds_dwordx4 v155, s[14:15]
	s_add_u32 s12, s12, 0x80
	s_addc_u32 s13, s13, 0
	s_add_u32 s14, s14, 0x80
	s_addc_u32 s15, s15, 0
	global_load_dwordx4 v[48:51], v[48:49], off
	global_load_dwordx4 v[76:79], v72, s[72:73]
	global_load_dwordx4 v[80:83], v73, s[72:73]
	global_load_dwordx4 v[84:87], v74, s[72:73]
	global_load_dwordx4 v[88:91], v75, s[72:73]
	global_load_dwordx4 v[92:95], v72, s[80:81]
	global_load_dwordx4 v[96:99], v73, s[80:81]
	global_load_dwordx4 v[100:103], v74, s[80:81]
	global_load_dwordx4 v[104:107], v75, s[80:81]
	v_mov_b32_e32 v16, 0
	v_mov_b32_e32 v17, 0
	v_mov_b32_e32 v18, 0
	v_mov_b32_e32 v19, 0
	v_mov_b32_e32 v20, 0
	v_mov_b32_e32 v21, 0
	v_mov_b32_e32 v22, 0
	v_mov_b32_e32 v23, 0
	v_mov_b32_e32 v24, 0
	v_mov_b32_e32 v25, 0
	v_mov_b32_e32 v26, 0
	v_mov_b32_e32 v27, 0
	v_mov_b32_e32 v28, 0
	v_mov_b32_e32 v29, 0
	v_mov_b32_e32 v30, 0
	v_mov_b32_e32 v31, 0
	v_mov_b32_e32 v0, 0
	v_mov_b32_e32 v1, 0
	v_mov_b32_e32 v2, 0
	v_mov_b32_e32 v3, 0
	v_mov_b32_e32 v4, 0
	v_mov_b32_e32 v5, 0
	v_mov_b32_e32 v6, 0
	v_mov_b32_e32 v7, 0
	v_mov_b32_e32 v8, 0
	v_mov_b32_e32 v9, 0
	v_mov_b32_e32 v10, 0
	v_mov_b32_e32 v11, 0
	v_mov_b32_e32 v12, 0
	v_mov_b32_e32 v13, 0
	v_mov_b32_e32 v14, 0
	v_mov_b32_e32 v15, 0
	v_add_u32_e32 v150, s16, v148
	v_add_u32_e32 v151, s16, v149
	s_mov_b32 s20, 0
	s_waitcnt vmcnt(13)
	s_barrier
	v_add_u32_e32 v152, v150, v211
	v_add_u32_e32 v153, v151, v211
	ds_read_b128 v[124:127], v152
	ds_read_b128 v[132:135], v153 offset:16384
	ds_read_b128 v[128:131], v152 offset:4096
.Lg3_loop:
	s_cmp_ge_u32 s20, 14
	s_cbranch_scc1 .Lg3_nodma
	s_add_i32 s21, s18, s19
	s_mov_b32 m0, s21
	s_nop 0
	global_load_lds_dwordx4 v154, s[12:13]
	s_add_i32 m0, s21, 0x2000
	s_nop 0
	global_load_lds_dwordx4 v155, s[12:13]
	s_add_i32 m0, s21, 0x4000
	s_nop 0
	global_load_lds_dwordx4 v154, s[14:15]
	s_add_i32 m0, s21, 0x6000
	s_nop 0
	global_load_lds_dwordx4 v155, s[14:15]
	s_add_u32 s12, s12, 0x80
	s_addc_u32 s13, s13, 0
	s_add_u32 s14, s14, 0x80
	s_addc_u32 s15, s15, 0
.Lg3_nodma:
	v_add_u32_e32 v152, v150, v212
	v_add_u32_e32 v153, v151, v212
	ds_read_b128 v[136:139], v152
	ds_read_b128 v[144:147], v153 offset:16384
	ds_read_b128 v[140:143], v152 offset:4096
	s_setprio 1
	s_waitcnt lgkmcnt(4)
	v_mfma_f32_32x32x16_bf16 v[16:31], v[124:127], v[132:135], v[16:31]
	s_waitcnt lgkmcnt(3)
	v_mfma_f32_32x32x16_bf16 v[0:15], v[128:131], v[132:135], v[0:15]
	s_setprio 0
	v_add_u32_e32 v152, v150, v213
	v_add_u32_e32 v153, v151, v213
	ds_read_b128 v[124:127], v152
	ds_read_b128 v[132:135], v153 offset:16384
	ds_read_b128 v[128:131], v152 offset:4096
	s_setprio 1
	s_waitcnt lgkmcnt(4)
	v_mfma_f32_32x32x16_bf16 v[16:31], v[136:139], v[144:147], v[16:31]
	s_waitcnt lgkmcnt(3)
	v_mfma_f32_32x32x16_bf16 v[0:15], v[140:143], v[144:147], v[0:15]
	s_setprio 0
	v_add_u32_e32 v152, v150, v214
	v_add_u32_e32 v153, v151, v214
	ds_read_b128 v[136:139], v152
	ds_read_b128 v[144:147], v153 offset:16384
	ds_read_b128 v[140:143], v152 offset:4096
	s_setprio 1
	s_waitcnt lgkmcnt(4)
	v_mfma_f32_32x32x16_bf16 v[16:31], v[124:127], v[132:135], v[16:31]
	s_waitcnt lgkmcnt(3)
	v_mfma_f32_32x32x16_bf16 v[0:15], v[128:131], v[132:135], v[0:15]
	s_setprio 0
	s_waitcnt lgkmcnt(0)
	s_cmp_ge_u32 s20, 14
	s_cbranch_scc1 .Lg3_w0
	s_cmp_eq_u32 s20, 0
	s_cbranch_scc0 .Lg3_w4
	s_waitcnt vmcnt(13)
	s_branch .Lg3_wd
.Lg3_w4:
	s_waitcnt vmcnt(4)
	s_branch .Lg3_wd

.Lg3_wd:
	s_barrier
	s_add_i32 s20, s20, 1
	s_mov_b32 s21, s16
	s_mov_b32 s16, s17
	s_mov_b32 s17, s18
	s_mov_b32 s18, s21
	s_cmp_eq_u32 s20, 16
	s_cbranch_scc1 .Lg3_done
	v_add_u32_e32 v150, s16, v148
	v_add_u32_e32 v151, s16, v149
	v_add_u32_e32 v152, v150, v211
	v_add_u32_e32 v153, v151, v211
	ds_read_b128 v[124:127], v152
	ds_read_b128 v[132:135], v153 offset:16384
	ds_read_b128 v[128:131], v152 offset:4096
	s_setprio 1
	v_mfma_f32_32x32x16_bf16 v[16:31], v[136:139], v[144:147], v[16:31]
	v_mfma_f32_32x32x16_bf16 v[0:15], v[140:143], v[144:147], v[0:15]
	s_setprio 0
	s_branch .Lg3_loop
.Lg3_done:
	s_setprio 1
	v_mfma_f32_32x32x16_bf16 v[16:31], v[136:139], v[144:147], v[16:31]
	v_mfma_f32_32x32x16_bf16 v[0:15], v[140:143], v[144:147], v[0:15]
	s_setprio 0
	s_nop 7
	s_nop 3
	ds_write_b32 v54, v16
	ds_write_b32 v54, v17 offset:272
	ds_write_b32 v54, v18 offset:544
	ds_write_b32 v54, v19 offset:816
	ds_write_b32 v54, v20 offset:2176
	ds_write_b32 v54, v21 offset:2448
	ds_write_b32 v54, v22 offset:2720
	ds_write_b32 v54, v23 offset:2992
	ds_write_b32 v54, v24 offset:4352
	ds_write_b32 v54, v25 offset:4624
	ds_write_b32 v54, v26 offset:4896
	ds_write_b32 v54, v27 offset:5168
	ds_write_b32 v54, v28 offset:6528
	ds_write_b32 v54, v29 offset:6800
	ds_write_b32 v54, v30 offset:7072
	ds_write_b32 v54, v31 offset:7344
	ds_read_b128 v[108:111], v35
	ds_read_b128 v[112:115], v35 offset:2176
	ds_read_b128 v[116:119], v35 offset:4352
	ds_read_b128 v[120:123], v35 offset:6528
	s_waitcnt lgkmcnt(3)
	v_pk_fma_f32 v[78:79], v[50:51], v[110:111], v[78:79]
	v_pk_fma_f32 v[76:77], v[48:49], v[108:109], v[76:77]
	global_store_dwordx4 v72, v[76:79], s[70:71]
	s_waitcnt lgkmcnt(2)
	v_pk_fma_f32 v[82:83], v[50:51], v[114:115], v[82:83]
	v_pk_fma_f32 v[80:81], v[48:49], v[112:113], v[80:81]
	global_store_dwordx4 v73, v[80:83], s[70:71]
	s_waitcnt lgkmcnt(1)
	v_pk_fma_f32 v[86:87], v[50:51], v[118:119], v[86:87]
	v_pk_fma_f32 v[84:85], v[48:49], v[116:117], v[84:85]
	global_store_dwordx4 v74, v[84:87], s[70:71]
	s_waitcnt lgkmcnt(0)
	v_pk_fma_f32 v[90:91], v[50:51], v[122:123], v[90:91]
	v_pk_fma_f32 v[88:89], v[48:49], v[120:121], v[88:89]
	global_store_dwordx4 v75, v[88:91], s[70:71]
	ds_write_b32 v54, v0
	ds_write_b32 v54, v1 offset:272
	ds_write_b32 v54, v2 offset:544
	ds_write_b32 v54, v3 offset:816
	ds_write_b32 v54, v4 offset:2176
	ds_write_b32 v54, v5 offset:2448
	ds_write_b32 v54, v6 offset:2720
	ds_write_b32 v54, v7 offset:2992
	ds_write_b32 v54, v8 offset:4352
	ds_write_b32 v54, v9 offset:4624
	ds_write_b32 v54, v10 offset:4896
	ds_write_b32 v54, v11 offset:5168
	ds_write_b32 v54, v12 offset:6528
	ds_write_b32 v54, v13 offset:6800
	ds_write_b32 v54, v14 offset:7072
	ds_write_b32 v54, v15 offset:7344
	ds_read_b128 v[108:111], v35
	ds_read_b128 v[112:115], v35 offset:2176
	ds_read_b128 v[116:119], v35 offset:4352
	ds_read_b128 v[120:123], v35 offset:6528
	s_waitcnt lgkmcnt(3)
	v_pk_fma_f32 v[94:95], v[50:51], v[110:111], v[94:95]
	v_pk_fma_f32 v[92:93], v[48:49], v[108:109], v[92:93]
	global_store_dwordx4 v72, v[92:95], s[100:101]
	s_waitcnt lgkmcnt(2)
	v_pk_fma_f32 v[98:99], v[50:51], v[114:115], v[98:99]
	v_pk_fma_f32 v[96:97], v[48:49], v[112:113], v[96:97]
	global_store_dwordx4 v73, v[96:99], s[100:101]
	s_waitcnt lgkmcnt(1)
	v_pk_fma_f32 v[102:103], v[50:51], v[118:119], v[102:103]
	v_pk_fma_f32 v[100:101], v[48:49], v[116:117], v[100:101]
	global_store_dwordx4 v74, v[100:103], s[100:101]
	s_waitcnt lgkmcnt(0)
	v_pk_fma_f32 v[106:107], v[50:51], v[122:123], v[106:107]
	v_pk_fma_f32 v[104:105], v[48:49], v[120:121], v[104:105]
	global_store_dwordx4 v75, v[104:107], s[100:101]
	s_add_i32 s2, s2, s86
	s_add_i32 s93, s93, s94
	s_cmp_lt_i32 s2, s33
	s_barrier
	s_cbranch_scc1 .LBB0_877
